# v49 + conv-FFN epilogues: 8 serialized row-ssq loads (load;vmcnt(0) x8) issued together up front into free VGPRs
# speedup vs baseline: 1.0182x; 1.0069x over previous
.LBB0_1133:
	s_mul_hi_i32 s0, s22, 0x3e0f83e1
	s_lshr_b32 s1, s0, 31
	s_ashr_i32 s0, s0, 3
	s_add_i32 s0, s0, s1
	s_mul_i32 s1, s0, 0xffffffdf
	s_add_i32 s1, s1, s22
	s_mul_i32 s18, s1, 0xfe
	s_add_i32 s18, s18, -2
	v_add_u32_e32 v197, s18, v177
	s_lshl_b32 s33, s0, 13
	v_readlane_b32 s100, v249, 28
	v_readlane_b32 s101, v249, 29
	v_mov_b32_e32 v252, v197
	v_cmp_gt_u32_e32 vcc, s73, v252
	s_and_saveexec_b64 s[98:99], vcc
	v_or_b32_e32 v252, s33, v252
	v_ashrrev_i32_e32 v253, 31, v252
	v_lshl_add_u64 v[252:253], v[252:253], 2, s[100:101]
	global_load_dword v242, v[252:253], off
	s_mov_b64 exec, s[98:99]
	v_add_u32_e32 v252, 16, v197
	v_cmp_gt_u32_e32 vcc, s73, v252
	s_and_saveexec_b64 s[98:99], vcc
	v_or_b32_e32 v252, s33, v252
	v_ashrrev_i32_e32 v253, 31, v252
	v_lshl_add_u64 v[252:253], v[252:253], 2, s[100:101]
	global_load_dword v243, v[252:253], off
	s_mov_b64 exec, s[98:99]
	v_add_u32_e32 v252, 32, v197
	v_cmp_gt_u32_e32 vcc, s73, v252
	s_and_saveexec_b64 s[98:99], vcc
	v_or_b32_e32 v252, s33, v252
	v_ashrrev_i32_e32 v253, 31, v252
	v_lshl_add_u64 v[252:253], v[252:253], 2, s[100:101]
	global_load_dword v244, v[252:253], off
	s_mov_b64 exec, s[98:99]
	v_add_u32_e32 v252, 48, v197
	v_cmp_gt_u32_e32 vcc, s73, v252
	s_and_saveexec_b64 s[98:99], vcc
	v_or_b32_e32 v252, s33, v252
	v_ashrrev_i32_e32 v253, 31, v252
	v_lshl_add_u64 v[252:253], v[252:253], 2, s[100:101]
	global_load_dword v245, v[252:253], off
	s_mov_b64 exec, s[98:99]
	v_add_u32_e32 v252, 128, v197
	v_cmp_gt_u32_e32 vcc, s73, v252
	s_and_saveexec_b64 s[98:99], vcc
	v_or_b32_e32 v252, s33, v252
	v_ashrrev_i32_e32 v253, 31, v252
	v_lshl_add_u64 v[252:253], v[252:253], 2, s[100:101]
	global_load_dword v246, v[252:253], off
	s_mov_b64 exec, s[98:99]
	v_add_u32_e32 v252, 144, v197
	v_cmp_gt_u32_e32 vcc, s73, v252
	s_and_saveexec_b64 s[98:99], vcc
	v_or_b32_e32 v252, s33, v252
	v_ashrrev_i32_e32 v253, 31, v252
	v_lshl_add_u64 v[252:253], v[252:253], 2, s[100:101]
	global_load_dword v247, v[252:253], off
	s_mov_b64 exec, s[98:99]
	v_add_u32_e32 v252, 160, v197
	v_cmp_gt_u32_e32 vcc, s73, v252
	s_and_saveexec_b64 s[98:99], vcc
	v_or_b32_e32 v252, s33, v252
	v_ashrrev_i32_e32 v253, 31, v252
	v_lshl_add_u64 v[252:253], v[252:253], 2, s[100:101]
	global_load_dword v250, v[252:253], off
	s_mov_b64 exec, s[98:99]
	v_add_u32_e32 v252, 176, v197
	v_cmp_gt_u32_e32 vcc, s73, v252
	s_and_saveexec_b64 s[98:99], vcc
	v_or_b32_e32 v252, s33, v252
	v_ashrrev_i32_e32 v253, 31, v252
	v_lshl_add_u64 v[252:253], v[252:253], 2, s[100:101]
	global_load_dword v251, v[252:253], off
	s_mov_b64 exec, s[98:99]
	v_cmp_gt_u32_e32 vcc, s73, v197
	v_mov_b32_e32 v202, 0
	v_mov_b32_e32 v204, 0
	s_and_saveexec_b64 s[14:15], vcc
	s_cbranch_execz .LBB0_1135
	v_or_b32_e32 v100, s33, v197
	v_readlane_b32 s0, v249, 28
	v_ashrrev_i32_e32 v101, 31, v100
	v_readlane_b32 s1, v249, 29
	s_nop 1
	v_lshl_add_u64 v[100:101], v[100:101], 2, s[0:1]
	s_waitcnt vmcnt(0)
	v_mov_b32_e32 v100, v242
	v_fmamk_f32 v100, v100, 0x3a800000, v237
	v_mul_f32_e32 v101, 0x4f800000, v100
	v_cmp_gt_f32_e32 vcc, s79, v100
	s_nop 1
	v_cndmask_b32_e32 v100, v100, v101, vcc
	v_sqrt_f32_e32 v101, v100
	s_nop 0
	v_add_u32_e32 v102, -1, v101
	v_add_u32_e32 v103, 1, v101
	v_fma_f32 v104, -v102, v101, v100
	v_fma_f32 v105, -v103, v101, v100
	v_cmp_ge_f32_e64 s[0:1], 0, v104
	s_nop 1
	v_cndmask_b32_e64 v101, v101, v102, s[0:1]
	v_cmp_lt_f32_e64 s[0:1], 0, v105
	s_nop 1
	v_cndmask_b32_e64 v101, v101, v103, s[0:1]
	v_mul_f32_e32 v102, 0x37800000, v101
	v_cndmask_b32_e32 v101, v101, v102, vcc
	v_cmp_class_f32_e32 vcc, v100, v238
	s_nop 1
	v_cndmask_b32_e32 v100, v101, v100, vcc
	v_div_scale_f32 v101, s[0:1], v100, v100, 1.0
	v_rcp_f32_e32 v102, v101
	v_div_scale_f32 v103, vcc, 1.0, v100, 1.0
	v_fma_f32 v104, -v101, v102, 1.0
	v_fmac_f32_e32 v102, v104, v102
	v_mul_f32_e32 v104, v103, v102
	v_fma_f32 v105, -v101, v104, v103
	v_fmac_f32_e32 v104, v105, v102
	v_fma_f32 v101, -v101, v104, v103
	v_div_fmas_f32 v101, v101, v102, v104
	v_div_fixup_f32 v204, v101, v100, 1.0
.LBB0_1135:
	s_or_b64 exec, exec, s[14:15]
	v_add_u32_e32 v100, 16, v197
	v_cmp_gt_u32_e32 vcc, s73, v100
	s_and_saveexec_b64 s[14:15], vcc
	s_cbranch_execz .LBB0_1137
	v_or_b32_e32 v100, s33, v100
	v_readlane_b32 s0, v249, 28
	v_ashrrev_i32_e32 v101, 31, v100
	v_readlane_b32 s1, v249, 29
	s_nop 1
	v_lshl_add_u64 v[100:101], v[100:101], 2, s[0:1]
	s_waitcnt vmcnt(0)
	v_mov_b32_e32 v100, v243
	v_fmamk_f32 v100, v100, 0x3a800000, v237
	v_mul_f32_e32 v101, 0x4f800000, v100
	v_cmp_gt_f32_e32 vcc, s79, v100
	s_nop 1
	v_cndmask_b32_e32 v100, v100, v101, vcc
	v_sqrt_f32_e32 v101, v100
	s_nop 0
	v_add_u32_e32 v102, -1, v101
	v_add_u32_e32 v103, 1, v101
	v_fma_f32 v104, -v102, v101, v100
	v_fma_f32 v105, -v103, v101, v100
	v_cmp_ge_f32_e64 s[0:1], 0, v104
	s_nop 1
	v_cndmask_b32_e64 v101, v101, v102, s[0:1]
	v_cmp_lt_f32_e64 s[0:1], 0, v105
	s_nop 1
	v_cndmask_b32_e64 v101, v101, v103, s[0:1]
	v_mul_f32_e32 v102, 0x37800000, v101
	v_cndmask_b32_e32 v101, v101, v102, vcc
	v_cmp_class_f32_e32 vcc, v100, v238
	s_nop 1
	v_cndmask_b32_e32 v100, v101, v100, vcc
	v_div_scale_f32 v101, s[0:1], v100, v100, 1.0
	v_rcp_f32_e32 v102, v101
	v_div_scale_f32 v103, vcc, 1.0, v100, 1.0
	v_fma_f32 v104, -v101, v102, 1.0
	v_fmac_f32_e32 v102, v104, v102
	v_mul_f32_e32 v104, v103, v102
	v_fma_f32 v105, -v101, v104, v103
	v_fmac_f32_e32 v104, v105, v102
	v_fma_f32 v101, -v101, v104, v103
	v_div_fmas_f32 v101, v101, v102, v104
	v_div_fixup_f32 v202, v101, v100, 1.0
.LBB0_1137:
	s_or_b64 exec, exec, s[14:15]
	v_add_u32_e32 v100, 32, v197
	v_cmp_gt_u32_e32 vcc, s73, v100
	v_mov_b32_e32 v128, 0
	v_mov_b32_e32 v200, 0
	s_and_saveexec_b64 s[14:15], vcc
	s_cbranch_execz .LBB0_1139
	v_or_b32_e32 v100, s33, v100
	v_readlane_b32 s0, v249, 28
	v_ashrrev_i32_e32 v101, 31, v100
	v_readlane_b32 s1, v249, 29
	s_nop 1
	v_lshl_add_u64 v[100:101], v[100:101], 2, s[0:1]
	s_waitcnt vmcnt(0)
	v_mov_b32_e32 v100, v244
	v_fmamk_f32 v100, v100, 0x3a800000, v237
	v_mul_f32_e32 v101, 0x4f800000, v100
	v_cmp_gt_f32_e32 vcc, s79, v100
	s_nop 1
	v_cndmask_b32_e32 v100, v100, v101, vcc
	v_sqrt_f32_e32 v101, v100
	s_nop 0
	v_add_u32_e32 v102, -1, v101
	v_add_u32_e32 v103, 1, v101
	v_fma_f32 v104, -v102, v101, v100
	v_fma_f32 v105, -v103, v101, v100
	v_cmp_ge_f32_e64 s[0:1], 0, v104
	s_nop 1
	v_cndmask_b32_e64 v101, v101, v102, s[0:1]
	v_cmp_lt_f32_e64 s[0:1], 0, v105
	s_nop 1
	v_cndmask_b32_e64 v101, v101, v103, s[0:1]
	v_mul_f32_e32 v102, 0x37800000, v101
	v_cndmask_b32_e32 v101, v101, v102, vcc
	v_cmp_class_f32_e32 vcc, v100, v238
	s_nop 1
	v_cndmask_b32_e32 v100, v101, v100, vcc
	v_div_scale_f32 v101, s[0:1], v100, v100, 1.0
	v_rcp_f32_e32 v102, v101
	v_div_scale_f32 v103, vcc, 1.0, v100, 1.0
	v_fma_f32 v104, -v101, v102, 1.0
	v_fmac_f32_e32 v102, v104, v102
	v_mul_f32_e32 v104, v103, v102
	v_fma_f32 v105, -v101, v104, v103
	v_fmac_f32_e32 v104, v105, v102
	v_fma_f32 v101, -v101, v104, v103
	v_div_fmas_f32 v101, v101, v102, v104
	v_div_fixup_f32 v200, v101, v100, 1.0
.LBB0_1139:
	s_or_b64 exec, exec, s[14:15]
	v_add_u32_e32 v100, 48, v197
	v_cmp_gt_u32_e32 vcc, s73, v100
	s_and_saveexec_b64 s[14:15], vcc
	s_cbranch_execz .LBB0_1141
	v_or_b32_e32 v100, s33, v100
	v_readlane_b32 s0, v249, 28
	v_ashrrev_i32_e32 v101, 31, v100
	v_readlane_b32 s1, v249, 29
	s_nop 1
	v_lshl_add_u64 v[100:101], v[100:101], 2, s[0:1]
	s_waitcnt vmcnt(0)
	v_mov_b32_e32 v100, v245
	v_fmamk_f32 v100, v100, 0x3a800000, v237
	v_mul_f32_e32 v101, 0x4f800000, v100
	v_cmp_gt_f32_e32 vcc, s79, v100
	s_nop 1
	v_cndmask_b32_e32 v100, v100, v101, vcc
	v_sqrt_f32_e32 v101, v100
	s_nop 0
	v_add_u32_e32 v102, -1, v101
	v_add_u32_e32 v103, 1, v101
	v_fma_f32 v104, -v102, v101, v100
	v_fma_f32 v105, -v103, v101, v100
	v_cmp_ge_f32_e64 s[0:1], 0, v104
	s_nop 1
	v_cndmask_b32_e64 v101, v101, v102, s[0:1]
	v_cmp_lt_f32_e64 s[0:1], 0, v105
	s_nop 1
	v_cndmask_b32_e64 v101, v101, v103, s[0:1]
	v_mul_f32_e32 v102, 0x37800000, v101
	v_cndmask_b32_e32 v101, v101, v102, vcc
	v_cmp_class_f32_e32 vcc, v100, v238
	s_nop 1
	v_cndmask_b32_e32 v100, v101, v100, vcc
	v_div_scale_f32 v101, s[0:1], v100, v100, 1.0
	v_rcp_f32_e32 v102, v101
	v_div_scale_f32 v103, vcc, 1.0, v100, 1.0
	v_fma_f32 v104, -v101, v102, 1.0
	v_fmac_f32_e32 v102, v104, v102
	v_mul_f32_e32 v104, v103, v102
	v_fma_f32 v105, -v101, v104, v103
	v_fmac_f32_e32 v104, v105, v102
	v_fma_f32 v101, -v101, v104, v103
	v_div_fmas_f32 v101, v101, v102, v104
	v_div_fixup_f32 v128, v101, v100, 1.0
.LBB0_1141:
	s_or_b64 exec, exec, s[14:15]
	v_add_u32_e32 v241, 0x80, v197
	v_cmp_gt_u32_e32 vcc, s73, v241
	v_mov_b32_e32 v196, 0
	v_mov_b32_e32 v198, 0
	s_and_saveexec_b64 s[14:15], vcc
	s_cbranch_execz .LBB0_1143
	v_or_b32_e32 v100, s33, v241
	v_readlane_b32 s0, v249, 28
	v_ashrrev_i32_e32 v101, 31, v100
	v_readlane_b32 s1, v249, 29
	s_nop 1
	v_lshl_add_u64 v[100:101], v[100:101], 2, s[0:1]
	s_waitcnt vmcnt(0)
	v_mov_b32_e32 v100, v246
	v_fmamk_f32 v100, v100, 0x3a800000, v237
	v_mul_f32_e32 v101, 0x4f800000, v100
	v_cmp_gt_f32_e32 vcc, s79, v100
	s_nop 1
	v_cndmask_b32_e32 v100, v100, v101, vcc
	v_sqrt_f32_e32 v101, v100
	s_nop 0
	v_add_u32_e32 v102, -1, v101
	v_add_u32_e32 v103, 1, v101
	v_fma_f32 v104, -v102, v101, v100
	v_fma_f32 v105, -v103, v101, v100
	v_cmp_ge_f32_e64 s[0:1], 0, v104
	s_nop 1
	v_cndmask_b32_e64 v101, v101, v102, s[0:1]
	v_cmp_lt_f32_e64 s[0:1], 0, v105
	s_nop 1
	v_cndmask_b32_e64 v101, v101, v103, s[0:1]
	v_mul_f32_e32 v102, 0x37800000, v101
	v_cndmask_b32_e32 v101, v101, v102, vcc
	v_cmp_class_f32_e32 vcc, v100, v238
	s_nop 1
	v_cndmask_b32_e32 v100, v101, v100, vcc
	v_div_scale_f32 v101, s[0:1], v100, v100, 1.0
	v_rcp_f32_e32 v102, v101
	v_div_scale_f32 v103, vcc, 1.0, v100, 1.0
	v_fma_f32 v104, -v101, v102, 1.0
	v_fmac_f32_e32 v102, v104, v102
	v_mul_f32_e32 v104, v103, v102
	v_fma_f32 v105, -v101, v104, v103
	v_fmac_f32_e32 v104, v105, v102
	v_fma_f32 v101, -v101, v104, v103
	v_div_fmas_f32 v101, v101, v102, v104
	v_div_fixup_f32 v198, v101, v100, 1.0
.LBB0_1143:
	s_or_b64 exec, exec, s[14:15]
	v_add_u32_e32 v240, 0x90, v197
	v_cmp_gt_u32_e32 vcc, s73, v240
	s_and_saveexec_b64 s[14:15], vcc
	s_cbranch_execz .LBB0_1145
	v_or_b32_e32 v100, s33, v240
	v_readlane_b32 s0, v249, 28
	v_ashrrev_i32_e32 v101, 31, v100
	v_readlane_b32 s1, v249, 29
	s_nop 1
	v_lshl_add_u64 v[100:101], v[100:101], 2, s[0:1]
	s_waitcnt vmcnt(0)
	v_mov_b32_e32 v100, v247
	v_fmamk_f32 v100, v100, 0x3a800000, v237
	v_mul_f32_e32 v101, 0x4f800000, v100
	v_cmp_gt_f32_e32 vcc, s79, v100
	s_nop 1
	v_cndmask_b32_e32 v100, v100, v101, vcc
	v_sqrt_f32_e32 v101, v100
	s_nop 0
	v_add_u32_e32 v102, -1, v101
	v_add_u32_e32 v103, 1, v101
	v_fma_f32 v104, -v102, v101, v100
	v_fma_f32 v105, -v103, v101, v100
	v_cmp_ge_f32_e64 s[0:1], 0, v104
	s_nop 1
	v_cndmask_b32_e64 v101, v101, v102, s[0:1]
	v_cmp_lt_f32_e64 s[0:1], 0, v105
	s_nop 1
	v_cndmask_b32_e64 v101, v101, v103, s[0:1]
	v_mul_f32_e32 v102, 0x37800000, v101
	v_cndmask_b32_e32 v101, v101, v102, vcc
	v_cmp_class_f32_e32 vcc, v100, v238
	s_nop 1
	v_cndmask_b32_e32 v100, v101, v100, vcc
	v_div_scale_f32 v101, s[0:1], v100, v100, 1.0
	v_rcp_f32_e32 v102, v101
	v_div_scale_f32 v103, vcc, 1.0, v100, 1.0
	v_fma_f32 v104, -v101, v102, 1.0
	v_fmac_f32_e32 v102, v104, v102
	v_mul_f32_e32 v104, v103, v102
	v_fma_f32 v105, -v101, v104, v103
	v_fmac_f32_e32 v104, v105, v102
	v_fma_f32 v101, -v101, v104, v103
	v_div_fmas_f32 v101, v101, v102, v104
	v_div_fixup_f32 v196, v101, v100, 1.0
.LBB0_1145:
	s_or_b64 exec, exec, s[14:15]
	v_add_u32_e32 v205, 0xa0, v197
	v_cmp_gt_u32_e32 vcc, s73, v205
	v_mov_b32_e32 v130, 0
	v_mov_b32_e32 v194, 0
	s_and_saveexec_b64 s[14:15], vcc
	s_cbranch_execz .LBB0_1147
	v_or_b32_e32 v100, s33, v205
	v_readlane_b32 s0, v249, 28
	v_ashrrev_i32_e32 v101, 31, v100
	v_readlane_b32 s1, v249, 29
	s_nop 1
	v_lshl_add_u64 v[100:101], v[100:101], 2, s[0:1]
	s_waitcnt vmcnt(0)
	v_mov_b32_e32 v100, v250
	v_fmamk_f32 v100, v100, 0x3a800000, v237
	v_mul_f32_e32 v101, 0x4f800000, v100
	v_cmp_gt_f32_e32 vcc, s79, v100
	s_nop 1
	v_cndmask_b32_e32 v100, v100, v101, vcc
	v_sqrt_f32_e32 v101, v100
	s_nop 0
	v_add_u32_e32 v102, -1, v101
	v_add_u32_e32 v103, 1, v101
	v_fma_f32 v104, -v102, v101, v100
	v_fma_f32 v105, -v103, v101, v100
	v_cmp_ge_f32_e64 s[0:1], 0, v104
	s_nop 1
	v_cndmask_b32_e64 v101, v101, v102, s[0:1]
	v_cmp_lt_f32_e64 s[0:1], 0, v105
	s_nop 1
	v_cndmask_b32_e64 v101, v101, v103, s[0:1]
	v_mul_f32_e32 v102, 0x37800000, v101
	v_cndmask_b32_e32 v101, v101, v102, vcc
	v_cmp_class_f32_e32 vcc, v100, v238
	s_nop 1
	v_cndmask_b32_e32 v100, v101, v100, vcc
	v_div_scale_f32 v101, s[0:1], v100, v100, 1.0
	v_rcp_f32_e32 v102, v101
	v_div_scale_f32 v103, vcc, 1.0, v100, 1.0
	v_fma_f32 v104, -v101, v102, 1.0
	v_fmac_f32_e32 v102, v104, v102
	v_mul_f32_e32 v104, v103, v102
	v_fma_f32 v105, -v101, v104, v103
	v_fmac_f32_e32 v104, v105, v102
	v_fma_f32 v101, -v101, v104, v103
	v_div_fmas_f32 v101, v101, v102, v104
	v_div_fixup_f32 v194, v101, v100, 1.0
.LBB0_1147:
	s_or_b64 exec, exec, s[14:15]
	v_add_u32_e32 v203, 0xb0, v197
	v_cmp_gt_u32_e32 vcc, s73, v203
	s_and_saveexec_b64 s[14:15], vcc
	s_cbranch_execz .LBB0_1149
	v_or_b32_e32 v100, s33, v203
	v_readlane_b32 s0, v249, 28
	v_ashrrev_i32_e32 v101, 31, v100
	v_readlane_b32 s1, v249, 29
	s_nop 1
	v_lshl_add_u64 v[100:101], v[100:101], 2, s[0:1]
	s_waitcnt vmcnt(0)
	v_mov_b32_e32 v100, v251
	v_fmamk_f32 v100, v100, 0x3a800000, v237
	v_mul_f32_e32 v101, 0x4f800000, v100
	v_cmp_gt_f32_e32 vcc, s79, v100
	s_nop 1
	v_cndmask_b32_e32 v100, v100, v101, vcc
	v_sqrt_f32_e32 v101, v100
	s_nop 0
	v_add_u32_e32 v102, -1, v101
	v_add_u32_e32 v103, 1, v101
	v_fma_f32 v104, -v102, v101, v100
	v_fma_f32 v105, -v103, v101, v100
	v_cmp_ge_f32_e64 s[0:1], 0, v104
	s_nop 1
	v_cndmask_b32_e64 v101, v101, v102, s[0:1]
	v_cmp_lt_f32_e64 s[0:1], 0, v105
	s_nop 1
	v_cndmask_b32_e64 v101, v101, v103, s[0:1]
	v_mul_f32_e32 v102, 0x37800000, v101
	v_cndmask_b32_e32 v101, v101, v102, vcc
	v_cmp_class_f32_e32 vcc, v100, v238
	s_nop 1
	v_cndmask_b32_e32 v100, v101, v100, vcc
	v_div_scale_f32 v101, s[0:1], v100, v100, 1.0
	v_rcp_f32_e32 v102, v101
	v_div_scale_f32 v103, vcc, 1.0, v100, 1.0
	v_fma_f32 v104, -v101, v102, 1.0
	v_fmac_f32_e32 v102, v104, v102
	v_mul_f32_e32 v104, v103, v102
	v_fma_f32 v105, -v101, v104, v103
	v_fmac_f32_e32 v104, v105, v102
	v_fma_f32 v101, -v101, v104, v103
	v_div_fmas_f32 v101, v101, v102, v104
	v_div_fixup_f32 v130, v101, v100, 1.0

.LBB0_2236:
	s_mul_hi_i32 s0, s22, 0x3e0f83e1
	s_lshr_b32 s1, s0, 31
	s_ashr_i32 s0, s0, 3
	s_add_i32 s0, s0, s1
	s_mul_i32 s1, s0, 0xffffffdf
	s_add_i32 s1, s1, s22
	s_mul_i32 s18, s1, 0xfe
	s_add_i32 s18, s18, -2
	v_add_u32_e32 v195, s18, v177
	s_lshl_b32 s33, s0, 13
	v_mov_b32_e32 v252, v195
	v_cmp_gt_u32_e32 vcc, s79, v252
	s_and_saveexec_b64 s[98:99], vcc
	v_or_b32_e32 v252, s33, v252
	v_ashrrev_i32_e32 v253, 31, v252
	v_lshl_add_u64 v[252:253], v[252:253], 2, s[28:29]
	global_load_dword v242, v[252:253], off
	s_mov_b64 exec, s[98:99]
	v_add_u32_e32 v252, 16, v195
	v_cmp_gt_u32_e32 vcc, s79, v252
	s_and_saveexec_b64 s[98:99], vcc
	v_or_b32_e32 v252, s33, v252
	v_ashrrev_i32_e32 v253, 31, v252
	v_lshl_add_u64 v[252:253], v[252:253], 2, s[28:29]
	global_load_dword v243, v[252:253], off
	s_mov_b64 exec, s[98:99]
	v_add_u32_e32 v252, 32, v195
	v_cmp_gt_u32_e32 vcc, s79, v252
	s_and_saveexec_b64 s[98:99], vcc
	v_or_b32_e32 v252, s33, v252
	v_ashrrev_i32_e32 v253, 31, v252
	v_lshl_add_u64 v[252:253], v[252:253], 2, s[28:29]
	global_load_dword v244, v[252:253], off
	s_mov_b64 exec, s[98:99]
	v_add_u32_e32 v252, 48, v195
	v_cmp_gt_u32_e32 vcc, s79, v252
	s_and_saveexec_b64 s[98:99], vcc
	v_or_b32_e32 v252, s33, v252
	v_ashrrev_i32_e32 v253, 31, v252
	v_lshl_add_u64 v[252:253], v[252:253], 2, s[28:29]
	global_load_dword v245, v[252:253], off
	s_mov_b64 exec, s[98:99]
	v_add_u32_e32 v252, 128, v195
	v_cmp_gt_u32_e32 vcc, s79, v252
	s_and_saveexec_b64 s[98:99], vcc
	v_or_b32_e32 v252, s33, v252
	v_ashrrev_i32_e32 v253, 31, v252
	v_lshl_add_u64 v[252:253], v[252:253], 2, s[28:29]
	global_load_dword v246, v[252:253], off
	s_mov_b64 exec, s[98:99]
	v_add_u32_e32 v252, 144, v195
	v_cmp_gt_u32_e32 vcc, s79, v252
	s_and_saveexec_b64 s[98:99], vcc
	v_or_b32_e32 v252, s33, v252
	v_ashrrev_i32_e32 v253, 31, v252
	v_lshl_add_u64 v[252:253], v[252:253], 2, s[28:29]
	global_load_dword v247, v[252:253], off
	s_mov_b64 exec, s[98:99]
	v_add_u32_e32 v252, 160, v195
	v_cmp_gt_u32_e32 vcc, s79, v252
	s_and_saveexec_b64 s[98:99], vcc
	v_or_b32_e32 v252, s33, v252
	v_ashrrev_i32_e32 v253, 31, v252
	v_lshl_add_u64 v[252:253], v[252:253], 2, s[28:29]
	global_load_dword v250, v[252:253], off
	s_mov_b64 exec, s[98:99]
	v_add_u32_e32 v252, 176, v195
	v_cmp_gt_u32_e32 vcc, s79, v252
	s_and_saveexec_b64 s[98:99], vcc
	v_or_b32_e32 v252, s33, v252
	v_ashrrev_i32_e32 v253, 31, v252
	v_lshl_add_u64 v[252:253], v[252:253], 2, s[28:29]
	global_load_dword v251, v[252:253], off
	s_mov_b64 exec, s[98:99]
	v_cmp_gt_u32_e32 vcc, s79, v195
	v_mov_b32_e32 v200, 0
	v_mov_b32_e32 v202, 0
	s_and_saveexec_b64 s[14:15], vcc
	s_cbranch_execz .LBB0_2238
	v_or_b32_e32 v96, s33, v195
	v_ashrrev_i32_e32 v97, 31, v96
	v_lshl_add_u64 v[96:97], v[96:97], 2, s[28:29]
	s_waitcnt vmcnt(0)
	v_mov_b32_e32 v96, v242
	v_fmamk_f32 v96, v96, 0x3a800000, v237
	v_mul_f32_e32 v97, 0x4f800000, v96
	v_cmp_gt_f32_e32 vcc, s95, v96
	s_nop 1
	v_cndmask_b32_e32 v96, v96, v97, vcc
	v_sqrt_f32_e32 v97, v96
	s_nop 0
	v_add_u32_e32 v98, -1, v97
	v_add_u32_e32 v99, 1, v97
	v_fma_f32 v100, -v98, v97, v96
	v_fma_f32 v101, -v99, v97, v96
	v_cmp_ge_f32_e64 s[0:1], 0, v100
	s_nop 1
	v_cndmask_b32_e64 v97, v97, v98, s[0:1]
	v_cmp_lt_f32_e64 s[0:1], 0, v101
	s_nop 1
	v_cndmask_b32_e64 v97, v97, v99, s[0:1]
	v_mul_f32_e32 v98, 0x37800000, v97
	v_cndmask_b32_e32 v97, v97, v98, vcc
	v_cmp_class_f32_e32 vcc, v96, v238
	s_nop 1
	v_cndmask_b32_e32 v96, v97, v96, vcc
	v_div_scale_f32 v97, s[0:1], v96, v96, 1.0
	v_rcp_f32_e32 v98, v97
	v_div_scale_f32 v99, vcc, 1.0, v96, 1.0
	v_fma_f32 v100, -v97, v98, 1.0
	v_fmac_f32_e32 v98, v100, v98
	v_mul_f32_e32 v100, v99, v98
	v_fma_f32 v101, -v97, v100, v99
	v_fmac_f32_e32 v100, v101, v98
	v_fma_f32 v97, -v97, v100, v99
	v_div_fmas_f32 v97, v97, v98, v100
	v_div_fixup_f32 v202, v97, v96, 1.0
.LBB0_2238:
	s_or_b64 exec, exec, s[14:15]
	v_add_u32_e32 v96, 16, v195
	v_cmp_gt_u32_e32 vcc, s79, v96
	s_and_saveexec_b64 s[14:15], vcc
	s_cbranch_execz .LBB0_2240
	v_or_b32_e32 v96, s33, v96
	v_ashrrev_i32_e32 v97, 31, v96
	v_lshl_add_u64 v[96:97], v[96:97], 2, s[28:29]
	s_waitcnt vmcnt(0)
	v_mov_b32_e32 v96, v243
	v_fmamk_f32 v96, v96, 0x3a800000, v237
	v_mul_f32_e32 v97, 0x4f800000, v96
	v_cmp_gt_f32_e32 vcc, s95, v96
	s_nop 1
	v_cndmask_b32_e32 v96, v96, v97, vcc
	v_sqrt_f32_e32 v97, v96
	s_nop 0
	v_add_u32_e32 v98, -1, v97
	v_add_u32_e32 v99, 1, v97
	v_fma_f32 v100, -v98, v97, v96
	v_fma_f32 v101, -v99, v97, v96
	v_cmp_ge_f32_e64 s[0:1], 0, v100
	s_nop 1
	v_cndmask_b32_e64 v97, v97, v98, s[0:1]
	v_cmp_lt_f32_e64 s[0:1], 0, v101
	s_nop 1
	v_cndmask_b32_e64 v97, v97, v99, s[0:1]
	v_mul_f32_e32 v98, 0x37800000, v97
	v_cndmask_b32_e32 v97, v97, v98, vcc
	v_cmp_class_f32_e32 vcc, v96, v238
	s_nop 1
	v_cndmask_b32_e32 v96, v97, v96, vcc
	v_div_scale_f32 v97, s[0:1], v96, v96, 1.0
	v_rcp_f32_e32 v98, v97
	v_div_scale_f32 v99, vcc, 1.0, v96, 1.0
	v_fma_f32 v100, -v97, v98, 1.0
	v_fmac_f32_e32 v98, v100, v98
	v_mul_f32_e32 v100, v99, v98
	v_fma_f32 v101, -v97, v100, v99
	v_fmac_f32_e32 v100, v101, v98
	v_fma_f32 v97, -v97, v100, v99
	v_div_fmas_f32 v97, v97, v98, v100
	v_div_fixup_f32 v200, v97, v96, 1.0
.LBB0_2240:
	s_or_b64 exec, exec, s[14:15]
	v_add_u32_e32 v96, 32, v195
	v_cmp_gt_u32_e32 vcc, s79, v96
	v_mov_b32_e32 v128, 0
	v_mov_b32_e32 v198, 0
	s_and_saveexec_b64 s[14:15], vcc
	s_cbranch_execz .LBB0_2242
	v_or_b32_e32 v96, s33, v96
	v_ashrrev_i32_e32 v97, 31, v96
	v_lshl_add_u64 v[96:97], v[96:97], 2, s[28:29]
	s_waitcnt vmcnt(0)
	v_mov_b32_e32 v96, v244
	v_fmamk_f32 v96, v96, 0x3a800000, v237
	v_mul_f32_e32 v97, 0x4f800000, v96
	v_cmp_gt_f32_e32 vcc, s95, v96
	s_nop 1
	v_cndmask_b32_e32 v96, v96, v97, vcc
	v_sqrt_f32_e32 v97, v96
	s_nop 0
	v_add_u32_e32 v98, -1, v97
	v_add_u32_e32 v99, 1, v97
	v_fma_f32 v100, -v98, v97, v96
	v_fma_f32 v101, -v99, v97, v96
	v_cmp_ge_f32_e64 s[0:1], 0, v100
	s_nop 1
	v_cndmask_b32_e64 v97, v97, v98, s[0:1]
	v_cmp_lt_f32_e64 s[0:1], 0, v101
	s_nop 1
	v_cndmask_b32_e64 v97, v97, v99, s[0:1]
	v_mul_f32_e32 v98, 0x37800000, v97
	v_cndmask_b32_e32 v97, v97, v98, vcc
	v_cmp_class_f32_e32 vcc, v96, v238
	s_nop 1
	v_cndmask_b32_e32 v96, v97, v96, vcc
	v_div_scale_f32 v97, s[0:1], v96, v96, 1.0
	v_rcp_f32_e32 v98, v97
	v_div_scale_f32 v99, vcc, 1.0, v96, 1.0
	v_fma_f32 v100, -v97, v98, 1.0
	v_fmac_f32_e32 v98, v100, v98
	v_mul_f32_e32 v100, v99, v98
	v_fma_f32 v101, -v97, v100, v99
	v_fmac_f32_e32 v100, v101, v98
	v_fma_f32 v97, -v97, v100, v99
	v_div_fmas_f32 v97, v97, v98, v100
	v_div_fixup_f32 v198, v97, v96, 1.0
.LBB0_2242:
	s_or_b64 exec, exec, s[14:15]
	v_add_u32_e32 v96, 48, v195
	v_cmp_gt_u32_e32 vcc, s79, v96
	s_and_saveexec_b64 s[14:15], vcc
	s_cbranch_execz .LBB0_2244
	v_or_b32_e32 v96, s33, v96
	v_ashrrev_i32_e32 v97, 31, v96
	v_lshl_add_u64 v[96:97], v[96:97], 2, s[28:29]
	s_waitcnt vmcnt(0)
	v_mov_b32_e32 v96, v245
	v_fmamk_f32 v96, v96, 0x3a800000, v237
	v_mul_f32_e32 v97, 0x4f800000, v96
	v_cmp_gt_f32_e32 vcc, s95, v96
	s_nop 1
	v_cndmask_b32_e32 v96, v96, v97, vcc
	v_sqrt_f32_e32 v97, v96
	s_nop 0
	v_add_u32_e32 v98, -1, v97
	v_add_u32_e32 v99, 1, v97
	v_fma_f32 v100, -v98, v97, v96
	v_fma_f32 v101, -v99, v97, v96
	v_cmp_ge_f32_e64 s[0:1], 0, v100
	s_nop 1
	v_cndmask_b32_e64 v97, v97, v98, s[0:1]
	v_cmp_lt_f32_e64 s[0:1], 0, v101
	s_nop 1
	v_cndmask_b32_e64 v97, v97, v99, s[0:1]
	v_mul_f32_e32 v98, 0x37800000, v97
	v_cndmask_b32_e32 v97, v97, v98, vcc
	v_cmp_class_f32_e32 vcc, v96, v238
	s_nop 1
	v_cndmask_b32_e32 v96, v97, v96, vcc
	v_div_scale_f32 v97, s[0:1], v96, v96, 1.0
	v_rcp_f32_e32 v98, v97
	v_div_scale_f32 v99, vcc, 1.0, v96, 1.0
	v_fma_f32 v100, -v97, v98, 1.0
	v_fmac_f32_e32 v98, v100, v98
	v_mul_f32_e32 v100, v99, v98
	v_fma_f32 v101, -v97, v100, v99
	v_fmac_f32_e32 v100, v101, v98
	v_fma_f32 v97, -v97, v100, v99
	v_div_fmas_f32 v97, v97, v98, v100
	v_div_fixup_f32 v128, v97, v96, 1.0
.LBB0_2244:
	s_or_b64 exec, exec, s[14:15]
	v_add_u32_e32 v241, 0x80, v195
	v_cmp_gt_u32_e32 vcc, s79, v241
	v_mov_b32_e32 v194, 0
	v_mov_b32_e32 v196, 0
	s_and_saveexec_b64 s[14:15], vcc
	s_cbranch_execz .LBB0_2246
	v_or_b32_e32 v96, s33, v241
	v_ashrrev_i32_e32 v97, 31, v96
	v_lshl_add_u64 v[96:97], v[96:97], 2, s[28:29]
	s_waitcnt vmcnt(0)
	v_mov_b32_e32 v96, v246
	v_fmamk_f32 v96, v96, 0x3a800000, v237
	v_mul_f32_e32 v97, 0x4f800000, v96
	v_cmp_gt_f32_e32 vcc, s95, v96
	s_nop 1
	v_cndmask_b32_e32 v96, v96, v97, vcc
	v_sqrt_f32_e32 v97, v96
	s_nop 0
	v_add_u32_e32 v98, -1, v97
	v_add_u32_e32 v99, 1, v97
	v_fma_f32 v100, -v98, v97, v96
	v_fma_f32 v101, -v99, v97, v96
	v_cmp_ge_f32_e64 s[0:1], 0, v100
	s_nop 1
	v_cndmask_b32_e64 v97, v97, v98, s[0:1]
	v_cmp_lt_f32_e64 s[0:1], 0, v101
	s_nop 1
	v_cndmask_b32_e64 v97, v97, v99, s[0:1]
	v_mul_f32_e32 v98, 0x37800000, v97
	v_cndmask_b32_e32 v97, v97, v98, vcc
	v_cmp_class_f32_e32 vcc, v96, v238
	s_nop 1
	v_cndmask_b32_e32 v96, v97, v96, vcc
	v_div_scale_f32 v97, s[0:1], v96, v96, 1.0
	v_rcp_f32_e32 v98, v97
	v_div_scale_f32 v99, vcc, 1.0, v96, 1.0
	v_fma_f32 v100, -v97, v98, 1.0
	v_fmac_f32_e32 v98, v100, v98
	v_mul_f32_e32 v100, v99, v98
	v_fma_f32 v101, -v97, v100, v99
	v_fmac_f32_e32 v100, v101, v98
	v_fma_f32 v97, -v97, v100, v99
	v_div_fmas_f32 v97, v97, v98, v100
	v_div_fixup_f32 v196, v97, v96, 1.0
.LBB0_2246:
	s_or_b64 exec, exec, s[14:15]
	v_add_u32_e32 v240, 0x90, v195
	v_cmp_gt_u32_e32 vcc, s79, v240
	s_and_saveexec_b64 s[14:15], vcc
	s_cbranch_execz .LBB0_2248
	v_or_b32_e32 v96, s33, v240
	v_ashrrev_i32_e32 v97, 31, v96
	v_lshl_add_u64 v[96:97], v[96:97], 2, s[28:29]
	s_waitcnt vmcnt(0)
	v_mov_b32_e32 v96, v247
	v_fmamk_f32 v96, v96, 0x3a800000, v237
	v_mul_f32_e32 v97, 0x4f800000, v96
	v_cmp_gt_f32_e32 vcc, s95, v96
	s_nop 1
	v_cndmask_b32_e32 v96, v96, v97, vcc
	v_sqrt_f32_e32 v97, v96
	s_nop 0
	v_add_u32_e32 v98, -1, v97
	v_add_u32_e32 v99, 1, v97
	v_fma_f32 v100, -v98, v97, v96
	v_fma_f32 v101, -v99, v97, v96
	v_cmp_ge_f32_e64 s[0:1], 0, v100
	s_nop 1
	v_cndmask_b32_e64 v97, v97, v98, s[0:1]
	v_cmp_lt_f32_e64 s[0:1], 0, v101
	s_nop 1
	v_cndmask_b32_e64 v97, v97, v99, s[0:1]
	v_mul_f32_e32 v98, 0x37800000, v97
	v_cndmask_b32_e32 v97, v97, v98, vcc
	v_cmp_class_f32_e32 vcc, v96, v238
	s_nop 1
	v_cndmask_b32_e32 v96, v97, v96, vcc
	v_div_scale_f32 v97, s[0:1], v96, v96, 1.0
	v_rcp_f32_e32 v98, v97
	v_div_scale_f32 v99, vcc, 1.0, v96, 1.0
	v_fma_f32 v100, -v97, v98, 1.0
	v_fmac_f32_e32 v98, v100, v98
	v_mul_f32_e32 v100, v99, v98
	v_fma_f32 v101, -v97, v100, v99
	v_fmac_f32_e32 v100, v101, v98
	v_fma_f32 v97, -v97, v100, v99
	v_div_fmas_f32 v97, v97, v98, v100
	v_div_fixup_f32 v194, v97, v96, 1.0
.LBB0_2248:
	s_or_b64 exec, exec, s[14:15]
	v_add_u32_e32 v203, 0xa0, v195
	v_cmp_gt_u32_e32 vcc, s79, v203
	v_mov_b32_e32 v130, 0
	v_mov_b32_e32 v192, 0
	s_and_saveexec_b64 s[14:15], vcc
	s_cbranch_execz .LBB0_2250
	v_or_b32_e32 v96, s33, v203
	v_ashrrev_i32_e32 v97, 31, v96
	v_lshl_add_u64 v[96:97], v[96:97], 2, s[28:29]
	s_waitcnt vmcnt(0)
	v_mov_b32_e32 v96, v250
	v_fmamk_f32 v96, v96, 0x3a800000, v237
	v_mul_f32_e32 v97, 0x4f800000, v96
	v_cmp_gt_f32_e32 vcc, s95, v96
	s_nop 1
	v_cndmask_b32_e32 v96, v96, v97, vcc
	v_sqrt_f32_e32 v97, v96
	s_nop 0
	v_add_u32_e32 v98, -1, v97
	v_add_u32_e32 v99, 1, v97
	v_fma_f32 v100, -v98, v97, v96
	v_fma_f32 v101, -v99, v97, v96
	v_cmp_ge_f32_e64 s[0:1], 0, v100
	s_nop 1
	v_cndmask_b32_e64 v97, v97, v98, s[0:1]
	v_cmp_lt_f32_e64 s[0:1], 0, v101
	s_nop 1
	v_cndmask_b32_e64 v97, v97, v99, s[0:1]
	v_mul_f32_e32 v98, 0x37800000, v97
	v_cndmask_b32_e32 v97, v97, v98, vcc
	v_cmp_class_f32_e32 vcc, v96, v238
	s_nop 1
	v_cndmask_b32_e32 v96, v97, v96, vcc
	v_div_scale_f32 v97, s[0:1], v96, v96, 1.0
	v_rcp_f32_e32 v98, v97
	v_div_scale_f32 v99, vcc, 1.0, v96, 1.0
	v_fma_f32 v100, -v97, v98, 1.0
	v_fmac_f32_e32 v98, v100, v98
	v_mul_f32_e32 v100, v99, v98
	v_fma_f32 v101, -v97, v100, v99
	v_fmac_f32_e32 v100, v101, v98
	v_fma_f32 v97, -v97, v100, v99
	v_div_fmas_f32 v97, v97, v98, v100
	v_div_fixup_f32 v192, v97, v96, 1.0
.LBB0_2250:
	s_or_b64 exec, exec, s[14:15]
	v_add_u32_e32 v201, 0xb0, v195
	v_cmp_gt_u32_e32 vcc, s79, v201
	s_and_saveexec_b64 s[14:15], vcc
	s_cbranch_execz .LBB0_2252
	v_or_b32_e32 v96, s33, v201
	v_ashrrev_i32_e32 v97, 31, v96
	v_lshl_add_u64 v[96:97], v[96:97], 2, s[28:29]
	s_waitcnt vmcnt(0)
	v_mov_b32_e32 v96, v251
	v_fmamk_f32 v96, v96, 0x3a800000, v237
	v_mul_f32_e32 v97, 0x4f800000, v96
	v_cmp_gt_f32_e32 vcc, s95, v96
	s_nop 1
	v_cndmask_b32_e32 v96, v96, v97, vcc
	v_sqrt_f32_e32 v97, v96
	s_nop 0
	v_add_u32_e32 v98, -1, v97
	v_add_u32_e32 v99, 1, v97
	v_fma_f32 v100, -v98, v97, v96
	v_fma_f32 v101, -v99, v97, v96
	v_cmp_ge_f32_e64 s[0:1], 0, v100
	s_nop 1
	v_cndmask_b32_e64 v97, v97, v98, s[0:1]
	v_cmp_lt_f32_e64 s[0:1], 0, v101
	s_nop 1
	v_cndmask_b32_e64 v97, v97, v99, s[0:1]
	v_mul_f32_e32 v98, 0x37800000, v97
	v_cndmask_b32_e32 v97, v97, v98, vcc
	v_cmp_class_f32_e32 vcc, v96, v238
	s_nop 1
	v_cndmask_b32_e32 v96, v97, v96, vcc
	v_div_scale_f32 v97, s[0:1], v96, v96, 1.0
	v_rcp_f32_e32 v98, v97
	v_div_scale_f32 v99, vcc, 1.0, v96, 1.0
	v_fma_f32 v100, -v97, v98, 1.0
	v_fmac_f32_e32 v98, v100, v98
	v_mul_f32_e32 v100, v99, v98
	v_fma_f32 v101, -v97, v100, v99
	v_fmac_f32_e32 v100, v101, v98
	v_fma_f32 v97, -v97, v100, v99
	v_div_fmas_f32 v97, v97, v98, v100
	v_div_fixup_f32 v130, v97, v96, 1.0

	.amdhsa_kernel _Z8mega_fwd4Args
		.amdhsa_group_segment_fixed_size 0
		.amdhsa_private_segment_fixed_size 0
		.amdhsa_kernarg_size 456
		.amdhsa_user_sgpr_count 2
		.amdhsa_user_sgpr_dispatch_ptr 0
		.amdhsa_user_sgpr_queue_ptr 0
		.amdhsa_user_sgpr_kernarg_segment_ptr 1
		.amdhsa_user_sgpr_dispatch_id 0
		.amdhsa_user_sgpr_kernarg_preload_length 0
		.amdhsa_user_sgpr_kernarg_preload_offset 0
		.amdhsa_user_sgpr_private_segment_size 0
		.amdhsa_uses_dynamic_stack 0
		.amdhsa_enable_private_segment 0
		.amdhsa_system_sgpr_workgroup_id_x 1
		.amdhsa_system_sgpr_workgroup_id_y 0
		.amdhsa_system_sgpr_workgroup_id_z 0
		.amdhsa_system_sgpr_workgroup_info 0
		.amdhsa_system_vgpr_workitem_id 2
		.amdhsa_next_free_vgpr 256
		.amdhsa_next_free_sgpr 102
		.amdhsa_accum_offset 256
		.amdhsa_reserve_vcc 1
		.amdhsa_float_round_mode_32 0
		.amdhsa_float_round_mode_16_64 0
		.amdhsa_float_denorm_mode_32 3
		.amdhsa_float_denorm_mode_16_64 3
		.amdhsa_dx10_clamp 1
		.amdhsa_ieee_mode 1
		.amdhsa_fp16_overflow 0
		.amdhsa_tg_split 0
		.amdhsa_exception_fp_ieee_invalid_op 0
		.amdhsa_exception_fp_denorm_src 0
		.amdhsa_exception_fp_ieee_div_zero 0
		.amdhsa_exception_fp_ieee_overflow 0
		.amdhsa_exception_fp_ieee_underflow 0
		.amdhsa_exception_fp_ieee_inexact 0
		.amdhsa_exception_int_div_zero 0
	.end_amdhsa_kernel

amdhsa.kernels:
  - .agpr_count:     0
    .args:
      - .offset:         0
        .size:           200
        .value_kind:     by_value
      - .offset:         200
        .size:           4
        .value_kind:     hidden_block_count_x
      - .offset:         204
        .size:           4
        .value_kind:     hidden_block_count_y
      - .offset:         208
        .size:           4
        .value_kind:     hidden_block_count_z
      - .offset:         212
        .size:           2
        .value_kind:     hidden_group_size_x
      - .offset:         214
        .size:           2
        .value_kind:     hidden_group_size_y
      - .offset:         216
        .size:           2
        .value_kind:     hidden_group_size_z
      - .offset:         218
        .size:           2
        .value_kind:     hidden_remainder_x
      - .offset:         220
        .size:           2
        .value_kind:     hidden_remainder_y
      - .offset:         222
        .size:           2
        .value_kind:     hidden_remainder_z
      - .offset:         240
        .size:           8
        .value_kind:     hidden_global_offset_x
      - .offset:         248
        .size:           8
        .value_kind:     hidden_global_offset_y
      - .offset:         256
        .size:           8
        .value_kind:     hidden_global_offset_z
      - .offset:         264
        .size:           2
        .value_kind:     hidden_grid_dims
      - .offset:         288
        .size:           8
        .value_kind:     hidden_multigrid_sync_arg
      - .offset:         320
        .size:           4
        .value_kind:     hidden_dynamic_lds_size
    .group_segment_fixed_size: 0
    .kernarg_segment_align: 8
    .kernarg_segment_size: 456
    .language:       OpenCL C
    .language_version:
      - 2
      - 0
    .max_flat_workgroup_size: 512
    .name:           _Z8mega_fwd4Args
    .private_segment_fixed_size: 0
    .sgpr_count:     108
    .sgpr_spill_count: 89
    .symbol:         _Z8mega_fwd4Args.kd
    .uniform_work_group_size: 1
    .uses_dynamic_stack: false
    .vgpr_count:     256
    .vgpr_spill_count: 0
    .wavefront_size: 64
